# C-unit prologue: spurious full wait between Q loads removed; first NORM pass: param loads hoisted into one batch
# speedup vs baseline: 1.0199x; 1.0016x over previous
.LBB0_92:
	flat_load_dwordx4 v[22:25], v[12:13]
	flat_load_dwordx4 v[26:29], v[12:13] offset:1024
	flat_load_dwordx4 v[0:3], v[12:13] offset:3072
	flat_load_dwordx4 v[4:7], v[12:13] offset:2048
	s_ashr_i32 s20, s6, 11
	v_mov_b32_e32 v30, v220
	s_waitcnt lgkmcnt(0)
	s_mov_b64 s[14:15], s[8:9]
	s_mulk_i32 s20, 0xc00
	s_ashr_i32 s21, s20, 31
	v_lshlrev_b32_e32 v32, 2, v30
	v_lshl_add_u64 v[30:31], s[14:15], 0, v[8:9]
	v_mov_b32_e32 v136, v30
	v_mov_b32_e32 v137, v31
	s_lshl_b64 s[14:15], s[20:21], 2
	s_add_u32 s20, s4, s14
	s_addc_u32 s21, s5, s15
	s_add_u32 s14, s20, 0x1000
	s_addc_u32 s15, s21, 0
	v_lshl_add_u64 v[42:43], s[20:21], 0, v[8:9]
	v_lshl_add_u64 v[38:39], s[14:15], 0, v[8:9]
	v_mov_b32_e32 v138, v38
	v_mov_b32_e32 v139, v39
	v_bitop3_b32 v57, v32, s3, v20 bitop3:0x6c
	flat_load_dwordx4 v[30:33], v[30:31]
	s_mov_b64 s[18:19], s[8:9]
	flat_load_dwordx4 v[34:37], v[42:43]
	v_lshl_add_u64 v[44:45], s[14:15], 0, v[14:15]
	flat_load_dwordx4 v[38:41], v[38:39]
	global_load_dwordx4 v[100:103], v[138:139], off offset:1024
	global_load_dwordx4 v[104:107], v[136:137], off offset:1024
	global_load_dwordx4 v[108:111], v[42:43], off offset:1024
	global_load_dwordx4 v[112:115], v[138:139], off offset:2048
	global_load_dwordx4 v[116:119], v[136:137], off offset:2048
	global_load_dwordx4 v[120:123], v[42:43], off offset:2048
	global_load_dwordx4 v[124:127], v[138:139], off offset:3072
	global_load_dwordx4 v[128:131], v[136:137], off offset:3072
	global_load_dwordx4 v[132:135], v[42:43], off offset:3072
	s_add_i32 s6, s6, s72
	v_lshl_add_u64 v[12:13], v[12:13], 0, s[12:13]
	s_cmpk_gt_i32 s6, 0x3fff
	s_waitcnt vmcnt(0)
	v_pk_mul_f32 v[46:47], v[24:25], v[24:25]
	v_pk_mul_f32 v[48:49], v[22:23], v[22:23]
	v_pk_mul_f32 v[50:51], v[28:29], v[28:29]
	v_pk_mul_f32 v[52:53], v[26:27], v[26:27]
	v_pk_mov_b32 v[58:59], v[48:49], v[46:47] op_sel:[1,0]
	v_mov_b32_e32 v49, v47
	v_pk_mov_b32 v[46:47], v[52:53], v[50:51] op_sel:[1,0]
	v_mov_b32_e32 v53, v51
	v_mul_f32_e32 v54, v5, v5
	v_mul_f32_e32 v56, v7, v7
	v_pk_add_f32 v[48:49], v[58:59], v[48:49]
	v_pk_add_f32 v[46:47], v[46:47], v[52:53]
	v_mul_f32_e32 v60, v0, v0
	v_mul_f32_e32 v61, v1, v1
	v_mul_f32_e32 v62, v2, v2
	v_mul_f32_e32 v63, v3, v3
	v_pk_fma_f32 v[50:51], v[4:5], v[4:5], v[54:55] op_sel_hi:[1,1,0]
	v_pk_fma_f32 v[54:55], v[6:7], v[6:7], v[56:57] op_sel_hi:[1,1,0]
	v_pk_add_f32 v[48:49], v[48:49], v[48:49] op_sel:[0,1] op_sel_hi:[1,0]
	v_pk_add_f32 v[46:47], v[46:47], v[46:47] op_sel:[0,1] op_sel_hi:[1,0]
	v_mov_b32_e32 v51, v62
	v_mov_b32_e32 v55, v63
	v_mov_b32_e32 v49, v60
	v_mov_b32_e32 v47, v61
	v_pk_add_f32 v[50:51], v[50:51], v[54:55]
	v_pk_add_f32 v[46:47], v[48:49], v[46:47]
	s_waitcnt lgkmcnt(0)
	v_pk_add_f32 v[40:41], v[40:41], 1.0 op_sel_hi:[1,0]
	v_pk_add_f32 v[46:47], v[46:47], v[50:51]
	v_pk_add_f32 v[38:39], v[38:39], 1.0 op_sel_hi:[1,0]
	v_add_f32_e32 v46, v46, v47
	ds_swizzle_b32 v47, v46 offset:swizzle(SWAP,1)
	s_waitcnt lgkmcnt(0)
	v_add_f32_e32 v46, v46, v47
	ds_swizzle_b32 v47, v46 offset:swizzle(SWAP,2)
	s_waitcnt lgkmcnt(0)
	v_add_f32_e32 v46, v46, v47
	ds_swizzle_b32 v47, v46 offset:swizzle(SWAP,4)
	s_waitcnt lgkmcnt(0)
	v_add_f32_e32 v46, v46, v47
	ds_swizzle_b32 v47, v46 offset:swizzle(SWAP,8)
	s_waitcnt lgkmcnt(0)
	v_add_f32_e32 v46, v46, v47
	ds_swizzle_b32 v47, v46 offset:swizzle(SWAP,16)
	s_waitcnt lgkmcnt(0)
	v_add_f32_e32 v46, v46, v47
	ds_bpermute_b32 v47, v57, v46
	s_waitcnt lgkmcnt(0)
	v_add_f32_e32 v46, v46, v47
	v_fmamk_f32 v46, v46, 0x3a800000, v21
	v_mul_f32_e32 v47, 0x4b800000, v46
	v_cmp_gt_f32_e32 vcc, s7, v46
	s_nop 1
	v_cndmask_b32_e32 v46, v46, v47, vcc
	v_rsq_f32_e32 v46, v46
	s_nop 0
	v_mul_f32_e32 v47, 0x45800000, v46
	v_cndmask_b32_e32 v46, v46, v47, vcc
	v_pk_mul_f32 v[24:25], v[46:47], v[24:25] op_sel_hi:[0,1]
	v_pk_mul_f32 v[22:23], v[46:47], v[22:23] op_sel_hi:[0,1]
	v_pk_mul_f32 v[22:23], v[30:31], v[22:23]
	v_pk_mul_f32 v[24:25], v[32:33], v[24:25]
	v_pk_fma_f32 v[22:23], v[38:39], v[22:23], v[34:35]
	v_pk_fma_f32 v[24:25], v[40:41], v[24:25], v[36:37]
	v_bfe_u32 v30, v22, 16, 1
	v_bfe_u32 v32, v24, 16, 1
	v_bfe_u32 v31, v23, 16, 1
	v_bfe_u32 v33, v25, 16, 1
	v_add3_u32 v22, v22, v30, s16
	v_add3_u32 v24, v24, v32, s16
	v_add3_u32 v23, v23, v31, s16
	v_add3_u32 v25, v25, v33, s16
	v_lshrrev_b32_e32 v22, 16, v22
	v_lshrrev_b32_e32 v24, 16, v24
	v_and_or_b32 v22, v23, s17, v22
	v_and_or_b32 v23, v25, s17, v24
	flat_store_dwordx2 v[10:11], v[22:23]
	v_pk_mul_f32 v[28:29], v[46:47], v[28:29] op_sel_hi:[0,1]
	v_pk_mul_f32 v[26:27], v[46:47], v[26:27] op_sel_hi:[0,1]
	s_mov_b64 s[18:19], s[8:9]
	v_pk_mul_f32 v[6:7], v[46:47], v[6:7] op_sel_hi:[0,1]
	v_pk_mul_f32 v[4:5], v[46:47], v[4:5] op_sel_hi:[0,1]
	v_pk_mul_f32 v[2:3], v[46:47], v[2:3] op_sel_hi:[0,1]
	v_pk_mul_f32 v[0:1], v[46:47], v[0:1] op_sel_hi:[0,1]
	v_pk_add_f32 v[102:103], v[102:103], 1.0 op_sel_hi:[1,0]
	v_pk_add_f32 v[100:101], v[100:101], 1.0 op_sel_hi:[1,0]
	v_pk_mul_f32 v[26:27], v[104:105], v[26:27]
	v_pk_mul_f32 v[28:29], v[106:107], v[28:29]
	v_pk_fma_f32 v[100:101], v[100:101], v[26:27], v[108:109]
	v_pk_fma_f32 v[102:103], v[102:103], v[28:29], v[110:111]
	v_bfe_u32 v26, v100, 16, 1
	v_bfe_u32 v28, v102, 16, 1
	v_bfe_u32 v27, v101, 16, 1
	v_bfe_u32 v29, v103, 16, 1
	v_add3_u32 v100, v100, v26, s16
	v_add3_u32 v102, v102, v28, s16
	v_add3_u32 v101, v101, v27, s16
	v_add3_u32 v103, v103, v29, s16
	v_lshrrev_b32_e32 v100, 16, v100
	v_lshrrev_b32_e32 v102, 16, v102
	v_and_or_b32 v100, v101, s17, v100
	v_and_or_b32 v101, v103, s17, v102
	flat_store_dwordx2 v[10:11], v[100:101] offset:512
	s_mov_b64 s[18:19], s[8:9]
	v_pk_add_f32 v[114:115], v[114:115], 1.0 op_sel_hi:[1,0]
	v_pk_add_f32 v[112:113], v[112:113], 1.0 op_sel_hi:[1,0]
	v_pk_mul_f32 v[4:5], v[116:117], v[4:5]
	v_pk_mul_f32 v[6:7], v[118:119], v[6:7]
	v_pk_fma_f32 v[4:5], v[112:113], v[4:5], v[120:121]
	v_pk_fma_f32 v[6:7], v[114:115], v[6:7], v[122:123]
	v_bfe_u32 v112, v4, 16, 1
	v_bfe_u32 v114, v6, 16, 1
	v_bfe_u32 v113, v5, 16, 1
	v_bfe_u32 v115, v7, 16, 1
	v_add3_u32 v4, v4, v112, s16
	v_add3_u32 v6, v6, v114, s16
	v_add3_u32 v5, v5, v113, s16
	v_add3_u32 v7, v7, v115, s16
	v_lshrrev_b32_e32 v4, 16, v4
	v_lshrrev_b32_e32 v6, 16, v6
	v_and_or_b32 v4, v5, s17, v4
	v_and_or_b32 v5, v7, s17, v6
	flat_store_dwordx2 v[10:11], v[4:5] offset:1024
	v_pk_add_f32 v[126:127], v[126:127], 1.0 op_sel_hi:[1,0]
	v_pk_add_f32 v[124:125], v[124:125], 1.0 op_sel_hi:[1,0]
	v_pk_mul_f32 v[0:1], v[128:129], v[0:1]
	v_pk_mul_f32 v[2:3], v[130:131], v[2:3]
	v_pk_fma_f32 v[0:1], v[124:125], v[0:1], v[132:133]
	v_pk_fma_f32 v[2:3], v[126:127], v[2:3], v[134:135]
	v_bfe_u32 v124, v0, 16, 1
	v_bfe_u32 v126, v2, 16, 1
	v_bfe_u32 v125, v1, 16, 1
	v_bfe_u32 v127, v3, 16, 1
	v_add3_u32 v0, v0, v124, s16
	v_add3_u32 v2, v2, v126, s16
	v_add3_u32 v1, v1, v125, s16
	v_add3_u32 v3, v3, v127, s16
	v_lshrrev_b32_e32 v0, 16, v0
	v_lshrrev_b32_e32 v2, 16, v2
	v_and_or_b32 v0, v1, s17, v0
	v_and_or_b32 v1, v3, s17, v2
	flat_store_dwordx2 v[10:11], v[0:1] offset:1536
	v_lshl_add_u64 v[10:11], v[10:11], 0, s[10:11]
	s_cbranch_scc0 .LBB0_92

.LBB0_441:
	s_abs_i32 s1, s3
	s_mul_hi_u32 s4, s1, s51
	s_mul_i32 s5, s4, s48
	s_ashr_i32 s0, s3, 31
	s_sub_i32 s1, s1, s5
	s_xor_b32 s0, s0, s49
	s_add_i32 s5, s4, 1
	s_sub_i32 s30, s1, s48
	s_cmp_ge_u32 s1, s48
	s_cselect_b32 s4, s5, s4
	s_cselect_b32 s1, s30, s1
	s_add_i32 s5, s4, 1
	s_cmp_ge_u32 s1, s48
	s_cselect_b32 s1, s5, s4
	s_xor_b32 s1, s1, s0
	s_sub_i32 s33, s1, s0
	s_mul_i32 s0, s33, s39
	s_sub_i32 s0, s3, s0
	s_ashr_i32 s4, s33, 3
	s_ashr_i32 s5, s4, 31
	s_ashr_i32 s1, s0, 31
	s_and_b32 s52, s33, 7
	s_lshl_b64 s[4:5], s[4:5], s65
	s_lshl_b64 s[30:31], s[0:1], 8
	s_add_u32 s54, s4, s30
	s_addc_u32 s55, s5, s31
	s_mul_i32 s1, s55, 0x4200
	s_mul_hi_u32 s3, s54, 0x4200
	s_add_i32 s3, s3, s1
	s_mul_i32 s1, s54, 0x4200
	s_add_u32 s1, s84, s1
	s_addc_u32 s30, s85, s3
	s_lshl_b32 s3, s52, 7
	s_add_u32 s1, s1, s3
	s_addc_u32 s58, s30, 0
	s_mulk_i32 s5, 0x4200
	s_mul_hi_u32 s30, s4, 0x4200
	s_add_i32 s5, s30, s5
	s_mulk_i32 s4, 0x4200
	s_add_u32 s34, s84, s4
	s_addc_u32 s35, s85, s5
	s_add_u32 s30, s34, s3
	s_addc_u32 s31, s35, 0
	s_lshl_b32 s33, s33, 7
	v_readlane_b32 s68, v254, 0
	s_and_b32 s60, s33, 0x300
	v_readlane_b32 s69, v254, 1
	v_readlane_b32 s56, v254, 36
	s_add_u32 s34, s34, s60
	s_mov_b64 s[36:37], s[68:69]
	v_readlane_b32 s57, v254, 37
	s_addc_u32 s35, s35, 0
	s_lshl_b64 s[56:57], s[56:57], 2
	s_add_u32 s36, s36, s56
	v_mov_b32_e32 v64, v220
	s_addc_u32 s37, s37, s57
	v_mov_b32_e32 v41, v205
	v_readfirstlane_b32 s57, v64
	v_and_b32_e32 v233, 63, v64
	s_ashr_i32 s53, s57, 6
	s_lshl_b32 s56, s53, 5
	s_mul_i32 s33, s53, 0x84000
	v_mul_u32_u24_e32 v0, 0x2100, v233
	s_mul_hi_i32 s59, s56, 0x4200
	s_add_u32 s62, s1, s33
	v_lshlrev_b32_e32 v204, 1, v0
	s_addc_u32 s63, s58, s59
	v_lshl_add_u64 v[0:1], s[30:31], 0, v[204:205]
	s_lshl_b32 s30, s53, 3
	s_ashr_i32 s31, s30, 31
	s_lshl_b64 s[30:31], s[30:31], 1
	v_lshl_add_u64 v[42:43], v[0:1], 0, s[30:31]
	s_lshl_b32 s1, s53, 4
	v_bfe_u32 v0, v64, 2, 4
	v_and_or_b32 v0, s1, 48, v0
	v_mul_u32_u24_e32 v0, 0x2100, v0
	v_lshlrev_b32_e32 v40, 1, v0
	s_ashr_i32 s1, s57, 3
	v_lshl_add_u64 v[0:1], s[34:35], 0, v[40:41]
	s_and_b32 s34, s1, 0xffffffe0
	s_ashr_i32 s35, s34, 31
	v_lshlrev_b32_e32 v236, 3, v64
	s_lshl_b64 s[34:35], s[34:35], 1
	v_and_b32_e32 v237, 24, v236
	s_mov_b64 s[58:59], 0x2a00
	v_lshl_add_u64 v[0:1], v[0:1], 0, s[34:35]
	v_lshlrev_b32_e32 v2, 1, v237
	v_mov_b32_e32 v3, v205
	v_lshl_add_u64 v[214:215], v[42:43], 0, s[58:59]
	v_lshl_add_u64 v[44:45], v[0:1], 0, v[2:3]
	s_mov_b64 s[58:59], 0x2e00
	v_lshl_add_u64 v[216:217], v[44:45], 0, s[58:59]
	s_lshl_b32 s58, s53, 10
	s_cmp_lg_u32 0, -1
	s_cselect_b32 s1, 0, 0
	s_add_i32 s58, s58, s1
	s_mov_b32 s1, m0
	s_mov_b32 m0, s58
	s_nop 0
	global_load_lds_dwordx4 v[214:215], off
	s_mov_b32 m0, s1
	s_mov_b64 s[64:65], 0x2e80
	s_add_i32 s59, s58, 0x6000
	s_mov_b32 s1, m0
	s_mov_b32 m0, s59
	s_nop 0
	global_load_lds_dwordx4 v[216:217], off
	s_mov_b32 m0, s1
	v_lshl_add_u64 v[0:1], v[44:45], 0, s[64:65]
	s_mov_b64 s[64:65], 0x10aa00
	v_and_b32_e32 v234, 31, v64
	s_add_i32 s1, s58, 0x8000
	s_mov_b32 s33, m0
	s_mov_b32 m0, s1
	s_nop 0
	global_load_lds_dwordx4 v[0:1], off
	s_mov_b32 m0, s33
	v_lshl_add_u64 v[0:1], v[42:43], 0, s[64:65]
	s_add_i32 s1, s58, 0x2000
	s_mov_b32 s33, m0
	s_mov_b32 m0, s1
	s_nop 0
	global_load_lds_dwordx4 v[0:1], off
	s_mov_b32 m0, s33
	v_mul_u32_u24_e32 v0, 0x2100, v234
	v_bfe_u32 v235, v64, 5, 1
	v_lshlrev_b32_e32 v0, 1, v0
	v_lshl_or_b32 v0, v235, 4, v0
	v_mov_b32_e32 v1, v205
	v_lshl_add_u64 v[0:1], s[62:63], 0, v[0:1]
	s_mov_b64 s[62:63], 0x2600
	s_movk_i32 s1, 0x2000
	v_lshl_add_u64 v[2:3], v[0:1], 0, s[62:63]
	v_add_co_u32_e32 v0, vcc, s1, v0
	v_mov_b32_e32 v62, v220
	s_nop 0
	v_addc_co_u32_e32 v1, vcc, 0, v1, vcc
	flat_load_dwordx4 v[28:31], v[2:3] offset:32
	flat_load_dwordx4 v[66:69], v[2:3] offset:64
	flat_load_dwordx4 v[24:27], v[0:1] offset:1536
	flat_load_dwordx4 v[52:55], v[2:3] offset:96
	v_and_b32_e32 v0, 32, v64
	v_mov_b32_e32 v1, v205
	v_lshl_add_u64 v[32:33], s[36:37], 0, v[0:1]
	v_mov_b64_e32 v[12:13], s[10:11]
	v_mov_b32_e32 v63, v220
	v_mov_b64_e32 v[48:49], s[14:15]
	flat_load_dwordx4 v[20:23], v[32:33]
	flat_load_dwordx4 v[8:11], v[32:33] offset:16
	flat_load_dwordx4 v[4:7], v[32:33] offset:64
	flat_load_dwordx4 v[0:3], v[32:33] offset:80
	flat_load_dwordx2 v[46:47], v[12:13]
	s_nop 0
	flat_load_dwordx4 v[12:15], v[32:33] offset:128
	flat_load_dwordx4 v[16:19], v[32:33] offset:144
	flat_load_dwordx4 v[36:39], v[32:33] offset:192
	s_nop 0
	flat_load_dwordx4 v[32:35], v[32:33] offset:208
	flat_load_dwordx2 v[48:49], v[48:49]
	v_mov_b32_e32 v65, v220
	v_mov_b64_e32 v[50:51], s[16:17]
	flat_load_dwordx2 v[50:51], v[50:51]
	v_mov_b32_e32 v79, v220
	v_mov_b64_e32 v[56:57], s[18:19]
	flat_load_dwordx2 v[56:57], v[56:57]
	v_mov_b32_e32 v80, v220
	v_mov_b64_e32 v[58:59], s[20:21]
	flat_load_dwordx2 v[60:61], v[58:59]
	v_mov_b32_e32 v81, v220
	v_mov_b64_e32 v[58:59], s[22:23]
	flat_load_dwordx2 v[70:71], v[58:59]
	v_mov_b32_e32 v82, v220
	v_mov_b64_e32 v[58:59], s[24:25]
	flat_load_dwordx2 v[72:73], v[58:59]
	v_mov_b32_e32 v83, v220
	v_mov_b64_e32 v[58:59], s[26:27]
	flat_load_dwordx2 v[74:75], v[58:59]
	v_lshl_or_b32 v76, s0, 8, v234
	v_add_u32_e32 v76, s56, v76
	v_cvt_f32_i32_e32 v122, v76
	v_lshlrev_b32_e32 v58, 10, v235
	v_lshlrev_b32_e32 v59, 4, v234
	v_add3_u32 v239, 0, v58, v59
	v_lshlrev_b32_e32 v58, 2, v62
	v_bitop3_b32 v123, v58, s88, v227 bitop3:0x6c
	s_mov_b32 s0, 0x800000
	s_mov_b64 s[36:37], 0x212a00
	s_mov_b64 s[64:65], 0x31aa00
	s_mov_b32 s61, 1
	s_mov_b32 s62, 2
	s_mov_b32 s33, 5
	v_readlane_b32 s70, v254, 2
	v_readlane_b32 s71, v254, 3
	s_waitcnt vmcnt(0) lgkmcnt(0)
	v_and_b32_e32 v105, 0xffff0000, v29
	v_lshlrev_b32_e32 v104, 16, v29
	s_waitcnt vmcnt(0)
	v_and_b32_e32 v117, 0xffff0000, v25
	v_lshlrev_b32_e32 v116, 16, v25
	v_and_b32_e32 v25, 0xffff0000, v24
	v_lshlrev_b32_e32 v24, 16, v24
	v_pk_mul_f32 v[120:121], v[24:25], v[24:25]
	v_pk_mul_f32 v[118:119], v[116:117], v[116:117]
	v_mul_f32_e32 v46, v46, v122
	v_fract_f32_e32 v46, v46
	v_fmac_f32_e32 v46, v47, v122
	v_cos_f32_e32 v76, v46
	v_sin_f32_e32 v58, v46
	v_lshlrev_b32_e32 v46, 2, v63
	v_bitop3_b32 v124, v46, s88, v227 bitop3:0x6c
	v_mul_f32_e32 v46, v48, v122
	v_fract_f32_e32 v46, v46
	v_fmac_f32_e32 v46, v49, v122
	v_cos_f32_e32 v77, v46
	v_sin_f32_e32 v59, v46
	v_lshlrev_b32_e32 v46, 2, v65
	v_bitop3_b32 v65, v46, s88, v227 bitop3:0x6c
	v_mul_f32_e32 v46, v50, v122
	v_fract_f32_e32 v46, v46
	v_fmac_f32_e32 v46, v51, v122
	v_cos_f32_e32 v78, v46
	v_sin_f32_e32 v62, v46
	v_lshlrev_b32_e32 v46, 2, v79
	v_bitop3_b32 v125, v46, s88, v227 bitop3:0x6c
	v_mul_f32_e32 v46, v56, v122
	v_fract_f32_e32 v46, v46
	v_fmac_f32_e32 v46, v57, v122
	v_cos_f32_e32 v79, v46
	v_sin_f32_e32 v63, v46
	v_lshlrev_b32_e32 v46, 2, v80
	v_bitop3_b32 v126, v46, s88, v227 bitop3:0x6c
	v_mul_f32_e32 v46, v60, v122
	v_fract_f32_e32 v46, v46
	v_fmac_f32_e32 v46, v61, v122
	v_cos_f32_e32 v80, v46
	v_sin_f32_e32 v60, v46
	v_lshlrev_b32_e32 v46, 2, v81
	v_bitop3_b32 v127, v46, s88, v227 bitop3:0x6c
	v_mul_f32_e32 v46, v70, v122
	v_fract_f32_e32 v46, v46
	v_fmac_f32_e32 v46, v71, v122
	v_add_f32_e32 v71, v120, v121
	v_and_b32_e32 v111, 0xffff0000, v27
	v_lshlrev_b32_e32 v110, 16, v27
	v_and_b32_e32 v27, 0xffff0000, v26
	v_lshlrev_b32_e32 v26, 16, v26
	v_add_f32_e32 v71, v118, v71
	v_pk_mul_f32 v[114:115], v[26:27], v[26:27]
	v_add_f32_e32 v71, v119, v71
	v_add_f32_e32 v71, v114, v71
	v_pk_mul_f32 v[112:113], v[110:111], v[110:111]
	v_add_f32_e32 v71, v115, v71
	v_and_b32_e32 v29, 0xffff0000, v28
	v_lshlrev_b32_e32 v28, 16, v28
	v_add_f32_e32 v71, v112, v71
	v_pk_mul_f32 v[108:109], v[28:29], v[28:29]
	v_add_f32_e32 v71, v113, v71
	v_add_f32_e32 v71, v108, v71
	v_pk_mul_f32 v[106:107], v[104:105], v[104:105]
	v_add_f32_e32 v71, v109, v71
	v_and_b32_e32 v99, 0xffff0000, v31
	v_lshlrev_b32_e32 v98, 16, v31
	v_and_b32_e32 v31, 0xffff0000, v30
	v_lshlrev_b32_e32 v30, 16, v30
	v_add_f32_e32 v71, v106, v71
	v_pk_mul_f32 v[102:103], v[30:31], v[30:31]
	v_add_f32_e32 v71, v107, v71
	v_add_f32_e32 v71, v102, v71
	v_cos_f32_e32 v81, v46
	v_sin_f32_e32 v61, v46
	v_lshlrev_b32_e32 v46, 2, v82
	v_pk_mul_f32 v[100:101], v[98:99], v[98:99]
	v_add_f32_e32 v71, v103, v71
	v_bitop3_b32 v128, v46, s88, v227 bitop3:0x6c
	v_mul_f32_e32 v46, v72, v122
	v_and_b32_e32 v93, 0xffff0000, v67
	v_lshlrev_b32_e32 v92, 16, v67
	v_and_b32_e32 v67, 0xffff0000, v66
	v_lshlrev_b32_e32 v66, 16, v66
	v_add_f32_e32 v71, v100, v71
	v_fract_f32_e32 v46, v46
	v_pk_mul_f32 v[96:97], v[66:67], v[66:67]
	v_add_f32_e32 v71, v101, v71
	v_fmac_f32_e32 v46, v73, v122
	v_add_f32_e32 v71, v96, v71
	v_cos_f32_e32 v70, v46
	v_sin_f32_e32 v72, v46
	v_lshlrev_b32_e32 v46, 2, v83
	v_pk_mul_f32 v[94:95], v[92:93], v[92:93]
	v_add_f32_e32 v71, v97, v71
	v_bitop3_b32 v129, v46, s88, v227 bitop3:0x6c
	v_mul_f32_e32 v46, v74, v122
	v_and_b32_e32 v57, 0xffff0000, v68
	v_lshlrev_b32_e32 v56, 16, v68
	v_add_f32_e32 v71, v94, v71
	v_fract_f32_e32 v73, v46
	v_and_b32_e32 v47, 0xffff0000, v55
	v_lshlrev_b32_e32 v46, 16, v55
	v_and_b32_e32 v49, 0xffff0000, v54
	v_lshlrev_b32_e32 v48, 16, v54
	v_and_b32_e32 v55, 0xffff0000, v69
	v_lshlrev_b32_e32 v54, 16, v69
	v_pk_mul_f32 v[68:69], v[56:57], v[56:57]
	v_add_f32_e32 v71, v95, v71
	v_add_f32_e32 v68, v68, v71
	v_pk_mul_f32 v[90:91], v[54:55], v[54:55]
	v_add_f32_e32 v68, v69, v68
	v_and_b32_e32 v51, 0xffff0000, v53
	v_lshlrev_b32_e32 v50, 16, v53
	v_and_b32_e32 v53, 0xffff0000, v52
	v_lshlrev_b32_e32 v52, 16, v52
	v_add_f32_e32 v68, v90, v68
	v_pk_mul_f32 v[88:89], v[52:53], v[52:53]
	v_add_f32_e32 v68, v91, v68
	v_add_f32_e32 v68, v88, v68
	v_pk_mul_f32 v[86:87], v[50:51], v[50:51]
	v_add_f32_e32 v68, v89, v68
	v_add_f32_e32 v68, v86, v68
	v_pk_mul_f32 v[84:85], v[48:49], v[48:49]
	v_add_f32_e32 v68, v87, v68
	v_add_f32_e32 v68, v84, v68
	v_pk_mul_f32 v[82:83], v[46:47], v[46:47]
	v_add_f32_e32 v68, v85, v68
	v_add_f32_e32 v68, v82, v68
	v_add_f32_e32 v68, v83, v68
	ds_bpermute_b32 v69, v123, v68
	v_mov_b32_e32 v74, v220
	v_fmac_f32_e32 v73, v75, v122
	v_cos_f32_e32 v71, v73
	s_waitcnt lgkmcnt(0)
	v_add_f32_e32 v68, v68, v69
	v_fmamk_f32 v68, v68, 0x3c800000, v224
	v_mul_f32_e32 v69, 0x4b800000, v68
	v_cmp_gt_f32_e32 vcc, s0, v68
	v_cmp_gt_u32_e64 s[0:1], 32, v233
	v_sin_f32_e32 v73, v73
	v_cndmask_b32_e32 v68, v68, v69, vcc
	v_rsq_f32_e32 v68, v68
	v_lshlrev_b32_e32 v69, 2, v74
	v_bitop3_b32 v69, v69, s88, v227 bitop3:0x6c
	v_mul_f32_e32 v74, 0x45800000, v68
	v_cndmask_b32_e32 v68, v68, v74, vcc
	v_pk_mul_f32 v[20:21], v[20:21], v[68:69] op_sel_hi:[1,0]
	v_pk_mul_f32 v[4:5], v[4:5], v[68:69] op_sel_hi:[1,0]
	v_pk_mul_f32 v[20:21], v[20:21], v[24:25]
	v_pk_mul_f32 v[22:23], v[22:23], v[68:69] op_sel_hi:[1,0]
	v_pk_mul_f32 v[24:25], v[4:5], v[28:29]
	v_pk_mul_f32 v[4:5], v[6:7], v[68:69] op_sel_hi:[1,0]
	v_pk_mul_f32 v[0:1], v[0:1], v[68:69] op_sel_hi:[1,0]
	v_pk_mul_f32 v[22:23], v[22:23], v[116:117]
	v_pk_mul_f32 v[74:75], v[4:5], v[104:105]
	v_pk_mul_f32 v[82:83], v[0:1], v[30:31]
	v_pk_mul_f32 v[0:1], v[2:3], v[68:69] op_sel_hi:[1,0]
	ds_bpermute_b32 v2, v65, v21
	ds_bpermute_b32 v4, v124, v20
	ds_bpermute_b32 v6, v126, v23
	ds_bpermute_b32 v7, v125, v22
	v_pk_mul_f32 v[84:85], v[0:1], v[98:99]
	v_pk_mul_f32 v[0:1], v[12:13], v[68:69] op_sel_hi:[1,0]
	v_pk_mul_f32 v[8:9], v[8:9], v[68:69] op_sel_hi:[1,0]
	v_pk_mul_f32 v[66:67], v[0:1], v[66:67]
	v_pk_mul_f32 v[0:1], v[14:15], v[68:69] op_sel_hi:[1,0]
	s_waitcnt lgkmcnt(3)
	v_cndmask_b32_e64 v3, v2, -v2, s[0:1]
	v_pk_mul_f32 v[86:87], v[0:1], v[92:93]
	v_pk_mul_f32 v[0:1], v[76:77], v[20:21]
	s_waitcnt lgkmcnt(2)
	v_cndmask_b32_e64 v2, v4, -v4, s[0:1]
	v_pk_mul_f32 v[8:9], v[8:9], v[26:27]
	v_pk_mul_f32 v[10:11], v[10:11], v[68:69] op_sel_hi:[1,0]
	v_pk_fma_f32 v[4:5], v[58:59], v[2:3], v[0:1]
	v_pk_mul_f32 v[0:1], v[78:79], v[22:23]
	s_waitcnt lgkmcnt(1)
	v_cndmask_b32_e64 v3, v6, -v6, s[0:1]
	s_waitcnt lgkmcnt(0)
	v_cndmask_b32_e64 v2, v7, -v7, s[0:1]
	v_pk_mul_f32 v[10:11], v[10:11], v[110:111]
	v_pk_fma_f32 v[6:7], v[62:63], v[2:3], v[0:1]
	ds_bpermute_b32 v2, v128, v9
	ds_bpermute_b32 v12, v127, v8
	ds_bpermute_b32 v13, v69, v11
	ds_bpermute_b32 v14, v129, v10
	v_pk_mul_f32 v[0:1], v[80:81], v[8:9]
	s_waitcnt lgkmcnt(3)
	v_cndmask_b32_e64 v3, v2, -v2, s[0:1]
	s_waitcnt lgkmcnt(2)
	v_cndmask_b32_e64 v2, v12, -v12, s[0:1]
	v_pk_fma_f32 v[8:9], v[60:61], v[2:3], v[0:1]
	s_waitcnt lgkmcnt(1)
	v_cndmask_b32_e64 v1, v13, -v13, s[0:1]
	s_waitcnt lgkmcnt(0)
	v_cndmask_b32_e64 v0, v14, -v14, s[0:1]
	v_pk_mul_f32 v[0:1], v[72:73], v[0:1]
	v_pk_mul_f32 v[16:17], v[16:17], v[68:69] op_sel_hi:[1,0]
	v_pk_fma_f32 v[10:11], v[70:71], v[10:11], v[0:1]
	v_lshl_add_u64 v[0:1], v[42:43], 0, s[36:37]
	s_add_i32 s36, s58, 0x4000
	s_mov_b32 s37, m0
	s_mov_b32 m0, s36
	s_nop 0
	global_load_lds_dwordx4 v[0:1], off
	s_mov_b32 m0, s37
	s_mov_b32 s36, 0x3e38aa3b
	s_waitcnt vmcnt(4) lgkmcnt(0)
	s_barrier
	v_pk_mul_f32 v[4:5], v[4:5], s[36:37] op_sel_hi:[1,0]
	ds_read_b128 v[20:23], v239 offset:512
	ds_read_b128 v[0:3], v239
	v_cvt_pk_bf16_f32 v156, v4, v5
	v_pk_mul_f32 v[4:5], v[6:7], s[36:37] op_sel_hi:[1,0]
	v_pk_mul_f32 v[62:63], v[16:17], v[56:57]
	v_cvt_pk_bf16_f32 v157, v4, v5
	v_pk_mul_f32 v[4:5], v[8:9], s[36:37] op_sel_hi:[1,0]
	v_pk_mul_f32 v[16:17], v[18:19], v[68:69] op_sel_hi:[1,0]
	v_cvt_pk_bf16_f32 v158, v4, v5
	v_pk_mul_f32 v[4:5], v[10:11], s[36:37] op_sel_hi:[1,0]
	v_pk_mul_f32 v[70:71], v[16:17], v[54:55]
	v_cvt_pk_bf16_f32 v159, v4, v5
	v_pk_mul_f32 v[72:73], v[24:25], s[36:37] op_sel_hi:[1,0]
	ds_read_b128 v[54:57], v239 offset:2560
	ds_read_b128 v[58:61], v239 offset:2048
	s_waitcnt lgkmcnt(3)
	v_mfma_f32_32x32x16_bf16 v[16:31], v[20:23], v[156:159], 0
	v_cvt_pk_bf16_f32 v152, v72, v73
	v_mul_f32_e64 v72, v74, s36
	v_mul_f32_e64 v73, v75, s36
	v_mul_f32_e64 v36, v36, v68
	v_mul_f32_e64 v37, v37, v68
	v_cvt_pk_bf16_f32 v153, v72, v73
	v_pk_mul_f32 v[72:73], v[82:83], s[36:37] op_sel_hi:[1,0]
	v_pk_mul_f32 v[66:67], v[66:67], s[36:37] op_sel_hi:[1,0]
	v_cvt_pk_bf16_f32 v154, v72, v73
	s_waitcnt lgkmcnt(2)
	v_mfma_f32_32x32x16_bf16 v[0:15], v[0:3], v[156:159], 0
	v_mul_f32_e64 v72, v84, s36
	v_mul_f32_e64 v73, v85, s36
	v_cvt_pk_bf16_f32 v148, v66, v67
	v_cvt_pk_bf16_f32 v155, v72, v73
	v_mul_f32_e64 v32, v32, v68
	v_mul_f32_e64 v33, v33, v68
	s_waitcnt lgkmcnt(1)
	v_mfma_f32_32x32x16_bf16 v[16:31], v[54:57], v[152:155], v[16:31]
	v_mul_f32_e64 v54, v86, s36
	v_mul_f32_e64 v55, v87, s36
	v_cvt_pk_bf16_f32 v149, v54, v55
	v_mul_f32_e64 v54, v62, s36
	v_mul_f32_e64 v55, v63, s36
	v_cvt_pk_bf16_f32 v150, v54, v55
	v_pk_mul_f32 v[54:55], v[70:71], s[36:37] op_sel_hi:[1,0]
	s_waitcnt lgkmcnt(0)
	v_mfma_f32_32x32x16_bf16 v[0:15], v[58:61], v[152:155], v[0:15]
	v_mul_f32_e64 v58, v36, v52
	v_mul_f32_e64 v59, v37, v53
	v_mul_f32_e64 v36, v38, v68
	v_mul_f32_e64 v37, v39, v68
	v_cvt_pk_bf16_f32 v151, v54, v55
	v_pk_mul_f32 v[60:61], v[36:37], v[50:51]
	ds_read_b128 v[36:39], v239 offset:4608
	ds_read_b128 v[50:53], v239 offset:4096
	v_pk_mul_f32 v[54:55], v[58:59], s[36:37] op_sel_hi:[1,0]
	s_waitcnt lgkmcnt(1)
	v_mfma_f32_32x32x16_bf16 v[16:31], v[36:39], v[148:151], v[16:31]
	v_mul_f32_e64 v36, v60, s36
	v_mul_f32_e64 v37, v61, s36
	v_cvt_pk_bf16_f32 v144, v54, v55
	v_cvt_pk_bf16_f32 v145, v36, v37
	s_waitcnt lgkmcnt(0)
	v_mfma_f32_32x32x16_bf16 v[0:15], v[50:53], v[148:151], v[0:15]
	v_mul_f32_e64 v50, v32, v48
	v_mul_f32_e64 v51, v33, v49
	v_mul_f32_e64 v32, v34, v68
	v_mul_f32_e64 v33, v35, v68
	v_mul_f32_e64 v36, v50, s36
	v_mul_f32_e64 v37, v51, s36
	v_pk_mul_f32 v[52:53], v[32:33], v[46:47]
	ds_read_b128 v[32:35], v239 offset:6656
	ds_read_b128 v[46:49], v239 offset:6144
	v_cvt_pk_bf16_f32 v146, v36, v37
	v_pk_mul_f32 v[36:37], v[52:53], s[36:37] op_sel_hi:[1,0]
	s_waitcnt vmcnt(0) lgkmcnt(0)
	s_barrier
	s_mov_b32 s36, 0
	v_cvt_pk_bf16_f32 v147, v36, v37
	v_lshlrev_b32_e32 v36, 1, v64
	v_and_b32_e32 v240, 32, v36
	s_waitcnt lgkmcnt(1)
	v_mfma_f32_32x32x16_bf16 v[16:31], v[32:35], v[144:147], v[16:31]
	v_lshl_add_u64 v[32:33], v[42:43], 0, s[64:65]
	s_mov_b32 s37, m0
	s_mov_b32 m0, s58
	s_nop 0
	global_load_lds_dwordx4 v[32:33], off
	s_mov_b32 m0, s37
	s_mov_b64 s[64:65], 0x10ae00
	s_add_i32 s37, s58, 0xa000
	v_lshl_add_u64 v[32:33], v[44:45], 0, s[64:65]
	s_mov_b32 s63, m0
	s_mov_b32 m0, s37
	s_nop 0
	global_load_lds_dwordx4 v[32:33], off
	s_mov_b32 m0, s63
	s_mov_b64 s[64:65], 0x10ae80
	s_waitcnt lgkmcnt(0)
	v_mfma_f32_32x32x16_bf16 v[0:15], v[46:49], v[144:147], v[0:15]
	s_add_i32 s37, s58, 0xc000
	v_lshl_add_u64 v[32:33], v[44:45], 0, s[64:65]
	s_mov_b32 s63, m0
	s_mov_b32 m0, s37
	s_nop 0
	global_load_lds_dwordx4 v[32:33], off
	s_mov_b32 m0, s63
	s_add_u32 s37, s34, s60
	s_addc_u32 s63, s35, 0
	ds_read_b128 v[188:191], v239 offset:8192
	ds_read_b128 v[180:183], v239 offset:8704
	ds_read_b128 v[184:187], v239 offset:10240
	ds_read_b128 v[176:179], v239 offset:10752
	ds_read_b128 v[172:175], v239 offset:12288
	ds_read_b128 v[168:171], v239 offset:12800
	ds_read_b128 v[164:167], v239 offset:14336
	ds_read_b128 v[160:163], v239 offset:14848
	s_add_u32 s3, s3, s30
	s_addc_u32 s31, 0, s31
	s_add_u32 s30, s6, s3
	s_addc_u32 s31, s7, s31
	v_lshlrev_b32_e32 v36, 4, v64
	s_add_u32 s3, s4, s60
	v_exp_f32_e32 v82, v2
	v_and_b32_e32 v2, 48, v36
	v_lshl_add_u64 v[194:195], s[30:31], 0, v[204:205]
	s_addc_u32 s30, s5, 0
	v_exp_f32_e32 v80, v0
	v_exp_f32_e32 v81, v1
	v_or_b32_e32 v0, s37, v2
	v_mov_b32_e32 v1, s63
	s_add_u32 s3, s34, s3
	v_exp_f32_e32 v64, v16
	v_exp_f32_e32 v65, v17
	v_exp_f32_e32 v66, v18
	v_exp_f32_e32 v67, v19
	v_exp_f32_e32 v68, v20
	v_exp_f32_e32 v69, v21
	v_exp_f32_e32 v70, v22
	v_exp_f32_e32 v71, v23
	v_exp_f32_e32 v72, v24
	v_exp_f32_e32 v73, v25
	v_exp_f32_e32 v74, v26
	v_exp_f32_e32 v75, v27
	v_exp_f32_e32 v76, v28
	v_exp_f32_e32 v77, v29
	v_exp_f32_e32 v78, v30
	v_exp_f32_e32 v79, v31
	v_exp_f32_e32 v83, v3
	v_exp_f32_e32 v84, v4
	v_exp_f32_e32 v85, v5
	v_exp_f32_e32 v86, v6
	v_exp_f32_e32 v87, v7
	v_exp_f32_e32 v88, v8
	v_exp_f32_e32 v89, v9
	v_exp_f32_e32 v90, v10
	v_exp_f32_e32 v91, v11
	v_exp_f32_e32 v92, v12
	v_exp_f32_e32 v93, v13
	v_exp_f32_e32 v94, v14
	v_exp_f32_e32 v95, v15
	v_lshl_add_u64 v[0:1], v[0:1], 0, v[40:41]
	s_addc_u32 s30, s35, s30
	v_and_b32_e32 v37, 0xc0, v36
	s_waitcnt vmcnt(3) lgkmcnt(0)
	s_barrier
	v_lshl_add_u64 v[192:193], s[6:7], 0, v[0:1]
	v_or_b32_e32 v0, s3, v2
	v_mov_b32_e32 v1, s30
	v_lshl_or_b32 v238, v235, 8, v37
	v_add_u32_e32 v37, 0, v240
	v_lshl_add_u64 v[0:1], v[0:1], 0, v[40:41]
	v_mov_b32_e32 v204, 0
	v_add3_u32 v241, v37, v237, v238
	v_lshl_add_u64 v[96:97], s[28:29], 0, v[0:1]
	s_mov_b32 s60, 1
	v_mov_b32_e32 v0, 0
	v_mov_b32_e32 v1, v204
	v_mov_b32_e32 v2, v204
	v_mov_b32_e32 v3, v204
	v_mov_b32_e32 v4, v204
	v_mov_b32_e32 v5, v204
	v_mov_b32_e32 v6, v204
	v_mov_b32_e32 v7, v204
	v_mov_b32_e32 v8, v204
	v_mov_b32_e32 v9, v204
	v_mov_b32_e32 v10, v204
	v_mov_b32_e32 v11, v204
	v_mov_b32_e32 v12, v204
	v_mov_b32_e32 v13, v204
	v_mov_b32_e32 v14, v204
	v_mov_b32_e32 v15, v204
	v_mov_b32_e32 v16, 0
	v_mov_b32_e32 v17, v204
	v_mov_b32_e32 v18, v204
	v_mov_b32_e32 v19, v204
	v_mov_b32_e32 v20, v204
	v_mov_b32_e32 v21, v204
	v_mov_b32_e32 v22, v204
	v_mov_b32_e32 v23, v204
	v_mov_b32_e32 v24, v204
	v_mov_b32_e32 v25, v204
	v_mov_b32_e32 v26, v204
	v_mov_b32_e32 v27, v204
	v_mov_b32_e32 v28, v204
	v_mov_b32_e32 v29, v204
	v_mov_b32_e32 v30, v204
	v_mov_b32_e32 v31, v204
	v_mov_b32_e32 v32, 0
	v_mov_b32_e32 v33, v204
	v_mov_b32_e32 v34, v204
	v_mov_b32_e32 v35, v204
	v_mov_b32_e32 v36, v204
	v_mov_b32_e32 v37, v204
	v_mov_b32_e32 v38, v204
	v_mov_b32_e32 v39, v204
	v_mov_b32_e32 v40, v204
	v_mov_b32_e32 v41, v204
	v_mov_b32_e32 v42, v204
	v_mov_b32_e32 v43, v204
	v_mov_b32_e32 v44, v204
	v_mov_b32_e32 v45, v204
	v_mov_b32_e32 v46, v204
	v_mov_b32_e32 v47, v204
	v_mov_b32_e32 v48, 0
	v_mov_b32_e32 v49, v204
	v_mov_b32_e32 v50, v204
	v_mov_b32_e32 v51, v204
	v_mov_b32_e32 v52, v204
	v_mov_b32_e32 v53, v204
	v_mov_b32_e32 v54, v204
	v_mov_b32_e32 v55, v204
	v_mov_b32_e32 v56, v204
	v_mov_b32_e32 v57, v204
	v_mov_b32_e32 v58, v204
	v_mov_b32_e32 v59, v204
	v_mov_b32_e32 v60, v204
	v_mov_b32_e32 v61, v204
	v_mov_b32_e32 v62, v204
	v_mov_b32_e32 v63, v204
